# nt loads for the single-use f32 scan arrays and gate columns read by the RG-LRU B units
# speedup vs baseline: 1.0091x; 1.0004x over previous
.LBB0_1032:
	s_or_b64 exec, exec, s[6:7]
	s_and_b32 s13, s86, 7
	s_lshl_b32 s6, s14, 10
	s_lshl_b32 s7, s13, 7
	s_or_b32 s6, s6, s7
	v_lshlrev_b32_e32 v0, 2, v50
	s_add_i32 s10, s6, 0x1000
	s_lshl_b32 s12, s15, 6
	s_lshl_b32 s6, s15, 8
	v_and_b32_e32 v48, 60, v0
	s_waitcnt lgkmcnt(0)
	s_add_u32 s6, s8, s6
	v_lshlrev_b32_e32 v64, 2, v48
	s_addc_u32 s7, s9, 0
	v_lshl_add_u64 v[0:1], s[6:7], 0, v[64:65]
	s_mov_b64 s[6:7], 0x10800000
	v_lshl_add_u64 v[2:3], v[0:1], 0, s[6:7]
	s_mov_b64 s[6:7], 0x11800000
	v_lshl_add_u64 v[4:5], v[0:1], 0, s[6:7]
	s_mov_b64 s[6:7], 0x12800000
	v_lshl_add_u64 v[8:9], v[0:1], 0, s[6:7]
	v_ashrrev_i32_e32 v0, 4, v50
	v_add_u32_e32 v70, s10, v0
	v_ashrrev_i32_e32 v71, 31, v70
	v_lshlrev_b64 v[0:1], 10, v[70:71]
	v_lshl_add_u64 v[6:7], v[2:3], 0, v[0:1]
	v_lshl_add_u64 v[10:11], v[4:5], 0, v[0:1]
	s_barrier
	global_load_dwordx4 v[36:39], v[6:7], off nt
	global_load_dwordx4 v[40:43], v[10:11], off nt
	v_mov_b64_e32 v[10:11], s[8:9]
	v_mad_i64_i32 v[6:7], s[6:7], v70, s93, v[10:11]
	s_lshl_b32 s96, s15, 7
	v_lshl_add_u64 v[6:7], v[6:7], 0, s[96:97]
	v_lshlrev_b32_e32 v64, 1, v48
	v_lshl_add_u64 v[6:7], v[6:7], 0, v[64:65]
	s_mov_b32 s11, 0xae00000
	v_lshl_add_u64 v[0:1], v[8:9], 0, v[0:1]
	v_add_co_u32_e32 v6, vcc, s11, v6
	s_nop 1
	v_addc_co_u32_e32 v7, vcc, 0, v7, vcc
	global_load_dwordx4 v[44:47], v[0:1], off nt
	global_load_dwordx2 v[72:73], v[6:7], off offset:2560 nt
	v_add_u32_e32 v0, 0x200, v50
	v_ashrrev_i32_e32 v0, 4, v0
	v_add_u32_e32 v66, s10, v0
	v_ashrrev_i32_e32 v67, 31, v66
	v_lshlrev_b64 v[0:1], 10, v[66:67]
	v_lshl_add_u64 v[6:7], v[2:3], 0, v[0:1]
	v_lshl_add_u64 v[12:13], v[4:5], 0, v[0:1]
	global_load_dwordx4 v[24:27], v[6:7], off nt
	global_load_dwordx4 v[28:31], v[12:13], off nt
	v_mad_i64_i32 v[6:7], s[6:7], v66, s93, v[10:11]
	v_lshl_add_u64 v[6:7], v[6:7], 0, s[96:97]
	v_lshl_add_u64 v[6:7], v[6:7], 0, v[64:65]
	v_lshl_add_u64 v[0:1], v[8:9], 0, v[0:1]
	v_add_co_u32_e32 v6, vcc, s11, v6
	s_nop 1
	v_addc_co_u32_e32 v7, vcc, 0, v7, vcc
	global_load_dwordx4 v[32:35], v[0:1], off nt
	global_load_dwordx2 v[68:69], v[6:7], off offset:2560 nt
	v_add_u32_e32 v0, 0x400, v50
	v_ashrrev_i32_e32 v0, 4, v0
	v_add_u32_e32 v60, s10, v0
	v_ashrrev_i32_e32 v61, 31, v60
	v_lshlrev_b64 v[0:1], 10, v[60:61]
	v_lshl_add_u64 v[6:7], v[2:3], 0, v[0:1]
	v_lshl_add_u64 v[16:17], v[4:5], 0, v[0:1]
	global_load_dwordx4 v[12:15], v[6:7], off nt
	s_nop 0
	global_load_dwordx4 v[16:19], v[16:17], off nt
	v_mad_i64_i32 v[6:7], s[6:7], v60, s93, v[10:11]
	v_lshl_add_u64 v[6:7], v[6:7], 0, s[96:97]
	v_lshl_add_u64 v[6:7], v[6:7], 0, v[64:65]
	v_lshl_add_u64 v[0:1], v[8:9], 0, v[0:1]
	v_add_co_u32_e32 v6, vcc, s11, v6
	s_nop 1
	v_addc_co_u32_e32 v7, vcc, 0, v7, vcc
	global_load_dwordx4 v[20:23], v[0:1], off nt
	global_load_dwordx2 v[62:63], v[6:7], off offset:2560 nt
	v_add_u32_e32 v0, 0x600, v50
	v_ashrrev_i32_e32 v0, 4, v0
	v_add_u32_e32 v56, s10, v0
	v_mad_i64_i32 v[10:11], s[6:7], v56, s93, v[10:11]
	v_ashrrev_i32_e32 v57, 31, v56
	v_lshl_add_u64 v[10:11], v[10:11], 0, s[96:97]
	v_lshlrev_b64 v[52:53], 10, v[56:57]
	v_lshl_add_u64 v[10:11], v[10:11], 0, v[64:65]
	v_lshl_add_u64 v[0:1], v[2:3], 0, v[52:53]
	v_lshl_add_u64 v[4:5], v[4:5], 0, v[52:53]
	v_lshl_add_u64 v[8:9], v[8:9], 0, v[52:53]
	v_add_co_u32_e32 v52, vcc, 0xae00000, v10
	global_load_dwordx4 v[0:3], v[0:1], off nt
	s_nop 0
	global_load_dwordx4 v[4:7], v[4:5], off nt
	v_addc_co_u32_e32 v53, vcc, 0, v11, vcc
	global_load_dwordx4 v[8:11], v[8:9], off nt
	s_nop 0
	global_load_dwordx2 v[58:59], v[52:53], off offset:2560 nt
	s_movk_i32 s6, 0x80
	v_cmp_gt_i32_e32 vcc, s6, v50
	s_and_saveexec_b64 s[10:11], vcc
	s_cbranch_execz .LBB0_1034
	s_add_i32 s16, s16, s15
	s_lshl_b32 s6, s16, 10
	s_add_i32 s96, s6, 0x10000
	s_lshl_b64 s[6:7], s[96:97], 3
	s_add_u32 s6, s8, s6
	s_addc_u32 s7, s9, s7
	s_lshl_b32 s14, s14, 3
	s_lshl_b32 s15, s45, 1
	v_ashrrev_i32_e32 v52, 6, v50
	s_add_i32 s15, s15, s14
	v_add_u32_e32 v54, s15, v52
	s_load_dwordx2 s[14:15], s[0:1], 0x20
	v_and_b32_e32 v49, 63, v50
	v_ashrrev_i32_e32 v55, 31, v54
	v_or_b32_e32 v51, s12, v49
	v_lshlrev_b64 v[54:55], 10, v[54:55]
	s_waitcnt lgkmcnt(0)
	v_lshl_add_u64 v[54:55], s[14:15], 0, v[54:55]
	v_lshlrev_b32_e32 v74, 2, v51
	v_mov_b32_e32 v75, v65
	v_lshl_add_u64 v[54:55], v[54:55], 0, v[74:75]
	global_load_dword v51, v[54:55], off
	v_lshlrev_b32_e32 v54, 3, v49
	v_mov_b32_e32 v55, v65
	v_ashrrev_i32_e32 v53, 31, v52
	v_lshl_add_u64 v[54:55], s[6:7], 0, v[54:55]
	v_lshlrev_b64 v[52:53], 9, v[52:53]
	v_lshl_add_u64 v[52:53], v[54:55], 0, v[52:53]
	s_mov_b64 s[6:7], 0x13800000
	v_lshl_add_u64 v[54:55], v[52:53], 0, s[6:7]
	s_mov_b32 s6, 0x13801000
	v_add_co_u32_e32 v52, vcc, s6, v52
	s_nop 1
	v_addc_co_u32_e32 v53, vcc, 0, v53, vcc
	global_load_dwordx2 v[74:75], v[52:53], off offset:-4096 nt
	global_load_dwordx2 v[76:77], v[54:55], off offset:1024 nt
	global_load_dwordx2 v[78:79], v[54:55], off offset:2048 nt
	s_nop 0
	global_load_dwordx2 v[54:55], v[54:55], off offset:3072 nt
	s_nop 0
	global_load_dwordx2 v[80:81], v[52:53], off nt
	global_load_dwordx2 v[82:83], v[52:53], off offset:1024 nt
	global_load_dwordx2 v[84:85], v[52:53], off offset:2048 nt
	s_nop 0
	global_load_dwordx2 v[52:53], v[52:53], off offset:3072 nt
	v_cmp_lt_u32_e32 vcc, 63, v50
	s_waitcnt vmcnt(0)
	s_nop 0
	v_cndmask_b32_e32 v50, v75, v53, vcc
	v_cndmask_b32_e32 v52, v74, v52, vcc
	v_fmac_f32_e32 v50, v51, v52
	v_cndmask_b32_e64 v52, 1, 6, vcc
	v_cmp_eq_u32_e64 s[6:7], s13, v52
	v_cndmask_b32_e32 v52, v77, v85, vcc
	v_cndmask_b32_e32 v53, v76, v84, vcc
	v_fmac_f32_e32 v52, v53, v50
	v_cndmask_b32_e64 v50, v51, v50, s[6:7]
	v_cndmask_b32_e64 v51, 2, 5, vcc
	v_cmp_eq_u32_e64 s[6:7], s13, v51
	v_cndmask_b32_e32 v51, v79, v83, vcc
	v_cndmask_b32_e32 v53, v78, v82, vcc
	v_cndmask_b32_e64 v50, v50, v52, s[6:7]
	v_fmac_f32_e32 v51, v53, v52
	v_cndmask_b32_e64 v52, 3, 4, vcc
	v_cmp_eq_u32_e64 s[6:7], s13, v52
	v_cndmask_b32_e32 v52, v55, v81, vcc
	v_cndmask_b32_e32 v53, v54, v80, vcc
	v_cndmask_b32_e64 v50, v50, v51, s[6:7]
	v_fmac_f32_e32 v52, v53, v51
	v_cndmask_b32_e64 v51, 4, 3, vcc
	v_cmp_eq_u32_e64 s[6:7], s13, v51
	v_cndmask_b32_e32 v51, v81, v55, vcc
	v_cndmask_b32_e32 v53, v80, v54, vcc
	v_cndmask_b32_e64 v50, v50, v52, s[6:7]
	v_fmac_f32_e32 v51, v53, v52
	v_cndmask_b32_e64 v52, 5, 2, vcc
	v_cmp_eq_u32_e64 s[6:7], s13, v52
	v_cndmask_b32_e32 v52, v83, v79, vcc
	v_cndmask_b32_e32 v53, v82, v78, vcc
	v_cndmask_b32_e64 v50, v50, v51, s[6:7]
	v_fmac_f32_e32 v52, v53, v51
	v_cndmask_b32_e64 v51, 6, 1, vcc
	v_cmp_eq_u32_e64 s[6:7], s13, v51
	v_cndmask_b32_e32 v51, v85, v77, vcc
	v_cndmask_b32_e32 v53, v84, v76, vcc
	v_cndmask_b32_e64 v50, v50, v52, s[6:7]
	v_fmac_f32_e32 v51, v53, v52
	v_cndmask_b32_e64 v52, 7, 0, vcc
	v_cmp_eq_u32_e64 s[6:7], s13, v52
	s_nop 1
	v_cndmask_b32_e64 v50, v50, v51, s[6:7]
	s_add_i32 s6, 0, 0x100
	v_mov_b32_e32 v51, s6
	v_cndmask_b32_e32 v51, 0, v51, vcc
	v_lshl_add_u32 v49, v49, 2, v51
	ds_write_b32 v49, v50
